# v39_deadaddr
# baseline (speedup 1.0000x reference)
; __device__ __forceinline__ float bf_lo(unsigned w) { return __uint_as_float(w << 16); }
; __device__ __forceinline__ float bf_hi(unsigned w) { return __uint_as_float(w & 0xffff0000u); }
; __device__ __forceinline__ void phase_mid(const Params& p, int gw, int NGW, int lane) {
;     ...
;     for (int row = gw; row < MT; row += NGW) {
;         const float r1 = rsqrtf(wave_sum(SSQ[(size_t)lane * MT + row]) * (1.f / DM) + EPSN);
;         const u32x2* mr = (const u32x2*)(MO + (size_t)row * DM) + lane; const f32x4* xr = (const f32x4*)(x + (size_t)row * DM) + lane;
;         const f32x4* g1p = g1 + lane; const f32x4* g2p = g2 + lane;
;         asm volatile("" : "+v"(g1p), "+v"(g2p), "+v"(mr), "+v"(xr));
;         f32x4 h[16]; float ss = 0.f;
; #pragma unroll
;         for (int j = 0; j < 16; ++j) { const u32x2 mw = mr[64 * j]; const f32x4 mo = {bf_lo(mw.x), bf_hi(mw.x), bf_lo(mw.y), bf_hi(mw.y)}; h[j] = xr[64 * j] + mo * r1 * g1p[64 * j]; ss += (h[j][0] * h[j][0] + h[j][1] * h[j][1]) + (h[j][2] * h[j][2] + h[j][3] * h[j][3]); }
.LBB0_711:
	global_load_dword v26, v[10:11], off
	v_lshl_add_u64 v[20:21], v[0:1], 0, s[6:7]
	v_mov_b64_e32 v[14:15], v[4:5]
	v_mov_b64_e32 v[18:19], v[12:13]
	v_mov_b64_e32 v[16:17], v[2:3]
	flat_load_dwordx4 v[28:31], v[18:19]
	flat_load_dwordx4 v[32:35], v[18:19] offset:1024
	flat_load_dwordx4 v[36:39], v[16:17]
	flat_load_dwordx4 v[40:43], v[16:17] offset:1024
	flat_load_dwordx2 v[66:67], v[20:21]
	flat_load_dwordx2 v[68:69], v[20:21] offset:512
	flat_load_dwordx2 v[70:71], v[20:21] offset:1024
	flat_load_dwordx2 v[72:73], v[20:21] offset:1536
	flat_load_dwordx4 v[46:49], v[18:19] offset:2048
	flat_load_dwordx4 v[50:53], v[18:19] offset:3072
	flat_load_dwordx4 v[54:57], v[16:17] offset:2048
	flat_load_dwordx4 v[58:61], v[16:17] offset:3072
	v_add_co_u32_e32 v92, vcc, s9, v18
	flat_load_dwordx2 v[168:169], v[20:21] offset:2048
	flat_load_dwordx2 v[170:171], v[20:21] offset:2560
	flat_load_dwordx2 v[172:173], v[20:21] offset:3072
	flat_load_dwordx2 v[180:181], v[20:21] offset:3584
	v_addc_co_u32_e32 v93, vcc, 0, v19, vcc
	v_add_co_u32_e32 v100, vcc, s9, v16
	v_lshl_add_u64 v[24:25], v[6:7], 0, s[6:7]
	s_nop 0
	v_addc_co_u32_e32 v101, vcc, 0, v17, vcc
	v_add_co_u32_e32 v20, vcc, s9, v20
	v_lshl_add_u64 v[22:23], v[8:9], 0, s[6:7]
	s_nop 0
	v_addc_co_u32_e32 v21, vcc, 0, v21, vcc
	v_add_co_u32_e32 v124, vcc, s3, v18
	s_add_i32 s17, s17, s60
	s_nop 0
	v_addc_co_u32_e32 v125, vcc, 0, v19, vcc
	v_add_co_u32_e32 v132, vcc, s3, v16
	s_add_u32 s6, s6, s12
	s_nop 0
	v_addc_co_u32_e32 v133, vcc, 0, v17, vcc
	v_add_co_u32_e32 v156, vcc, s16, v18
	s_addc_u32 s7, s7, s13
	s_nop 0
	v_addc_co_u32_e32 v157, vcc, 0, v19, vcc
	v_add_co_u32_e32 v164, vcc, s16, v16
	v_lshl_add_u64 v[10:11], v[10:11], 0, s[4:5]
	s_nop 0
	v_addc_co_u32_e32 v165, vcc, 0, v17, vcc
	flat_load_dwordx2 v[182:183], v[20:21]
	flat_load_dwordx2 v[184:185], v[20:21] offset:512
	flat_load_dwordx2 v[186:187], v[20:21] offset:1024
	flat_load_dwordx2 v[188:189], v[20:21] offset:1536
	flat_load_dwordx2 v[190:191], v[20:21] offset:2048
	flat_load_dwordx2 v[194:195], v[20:21] offset:2560
	flat_load_dwordx4 v[16:19], v[92:93]
	flat_load_dwordx4 v[80:83], v[92:93] offset:1024
	flat_load_dwordx4 v[62:65], v[100:101]
	flat_load_dwordx4 v[84:87], v[100:101] offset:1024
	flat_load_dwordx2 v[196:197], v[20:21] offset:3072
	flat_load_dwordx4 v[88:91], v[92:93] offset:2048
	s_nop 0
	flat_load_dwordx4 v[92:95], v[92:93] offset:3072
	s_nop 0
	flat_load_dwordx2 v[20:21], v[20:21] offset:3584
	s_nop 0
	flat_load_dwordx4 v[96:99], v[100:101] offset:2048
	s_nop 0
	flat_load_dwordx4 v[100:103], v[100:101] offset:3072
	s_nop 0
	flat_load_dwordx4 v[104:107], v[124:125]
	flat_load_dwordx4 v[108:111], v[124:125] offset:1024
	flat_load_dwordx4 v[112:115], v[132:133]
	flat_load_dwordx4 v[116:119], v[132:133] offset:1024
	flat_load_dwordx4 v[120:123], v[124:125] offset:2048
	s_nop 0
	flat_load_dwordx4 v[124:127], v[124:125] offset:3072
	s_nop 0
	flat_load_dwordx4 v[128:131], v[132:133] offset:2048
	s_nop 0
	flat_load_dwordx4 v[132:135], v[132:133] offset:3072
	s_nop 0
	flat_load_dwordx4 v[136:139], v[156:157]
	flat_load_dwordx4 v[140:143], v[156:157] offset:1024
	flat_load_dwordx4 v[144:147], v[164:165]
	flat_load_dwordx4 v[148:151], v[164:165] offset:1024
	flat_load_dwordx4 v[152:155], v[156:157] offset:2048
	s_nop 0
	flat_load_dwordx4 v[156:159], v[156:157] offset:3072
	s_nop 0
	flat_load_dwordx4 v[160:163], v[164:165] offset:2048
	s_nop 0
	flat_load_dwordx4 v[164:167], v[164:165] offset:3072
	v_lshl_add_u64 v[12:13], v[12:13], 0, s[14:15]
	s_cmpk_lt_i32 s17, 0x2000
	s_waitcnt vmcnt(0) lgkmcnt(0)
	v_lshlrev_b32_e32 v198, 16, v66
	ds_bpermute_b32 v27, v45, v26
	v_and_b32_e32 v199, 0xffff0000, v66
	v_lshlrev_b32_e32 v66, 16, v67
	v_and_b32_e32 v67, 0xffff0000, v67
	v_lshlrev_b32_e32 v200, 16, v68
	s_waitcnt lgkmcnt(0)
	v_add_f32_e32 v26, v26, v27
	ds_bpermute_b32 v27, v74, v26
	v_and_b32_e32 v201, 0xffff0000, v68
	v_lshlrev_b32_e32 v68, 16, v69
	v_and_b32_e32 v69, 0xffff0000, v69
	v_lshlrev_b32_e32 v202, 16, v70
	s_waitcnt lgkmcnt(0)
	v_add_f32_e32 v26, v26, v27
	ds_bpermute_b32 v27, v75, v26
	v_and_b32_e32 v203, 0xffff0000, v70
	v_lshlrev_b32_e32 v70, 16, v71
	v_and_b32_e32 v71, 0xffff0000, v71
	v_lshlrev_b32_e32 v204, 16, v72
	s_waitcnt lgkmcnt(0)
	v_add_f32_e32 v26, v26, v27
	ds_bpermute_b32 v27, v76, v26
	v_and_b32_e32 v205, 0xffff0000, v72
	v_lshlrev_b32_e32 v72, 16, v73
	v_and_b32_e32 v73, 0xffff0000, v73
	v_lshlrev_b32_e32 v206, 16, v168
	s_waitcnt lgkmcnt(0)
	v_add_f32_e32 v26, v26, v27
	ds_bpermute_b32 v27, v77, v26
	v_and_b32_e32 v207, 0xffff0000, v168
	v_lshlrev_b32_e32 v168, 16, v169
	v_and_b32_e32 v169, 0xffff0000, v169
	v_lshlrev_b32_e32 v208, 16, v170
	s_waitcnt lgkmcnt(0)
	v_add_f32_e32 v26, v26, v27
	ds_bpermute_b32 v27, v78, v26
	v_and_b32_e32 v209, 0xffff0000, v170
	v_lshlrev_b32_e32 v170, 16, v171
	v_and_b32_e32 v171, 0xffff0000, v171
	v_lshlrev_b32_e32 v212, 16, v180
	s_waitcnt lgkmcnt(0)
; __device__ __forceinline__ float bf_lo(unsigned w) { return __uint_as_float(w << 16); }
; __device__ __forceinline__ float bf_hi(unsigned w) { return __uint_as_float(w & 0xffff0000u); }
; __device__ __forceinline__ void phase_mid(const Params& p, int gw, int NGW, int lane) {
;     ...
;         const float r1 = rsqrtf(wave_sum(SSQ[(size_t)lane * MT + row]) * (1.f / DM) + EPSN);
;         const u32x2* mr = (const u32x2*)(MO + (size_t)row * DM) + lane; const f32x4* xr = (const f32x4*)(x + (size_t)row * DM) + lane;
;         const f32x4* g1p = g1 + lane; const f32x4* g2p = g2 + lane;
;         asm volatile("" : "+v"(g1p), "+v"(g2p), "+v"(mr), "+v"(xr));
;         f32x4 h[16]; float ss = 0.f;
; #pragma unroll
;         for (int j = 0; j < 16; ++j) { const u32x2 mw = mr[64 * j]; const f32x4 mo = {bf_lo(mw.x), bf_hi(mw.x), bf_lo(mw.y), bf_hi(mw.y)}; h[j] = xr[64 * j] + mo * r1 * g1p[64 * j]; ss += (h[j][0] * h[j][0] + h[j][1] * h[j][1]) + (h[j][2] * h[j][2] + h[j][3] * h[j][3]); }
	v_add_f32_e32 v26, v26, v27
	v_fmamk_f32 v26, v26, 0x39800000, v79
	v_mul_f32_e32 v27, 0x4b800000, v26
	v_cmp_gt_f32_e32 vcc, s8, v26
	v_and_b32_e32 v213, 0xffff0000, v180
	v_lshlrev_b32_e32 v180, 16, v181
	v_cndmask_b32_e32 v26, v26, v27, vcc
	v_rsq_f32_e32 v26, v26
	v_and_b32_e32 v181, 0xffff0000, v181
	v_lshlrev_b32_e32 v214, 16, v182
	v_and_b32_e32 v215, 0xffff0000, v182
	v_mul_f32_e32 v27, 0x45800000, v26
	v_cndmask_b32_e32 v26, v26, v27, vcc
	v_lshlrev_b32_e32 v182, 16, v183
	v_and_b32_e32 v183, 0xffff0000, v183
	v_lshlrev_b32_e32 v218, 16, v186
	v_and_b32_e32 v219, 0xffff0000, v186
	v_lshlrev_b32_e32 v186, 16, v187
	v_and_b32_e32 v187, 0xffff0000, v187
	v_lshlrev_b32_e32 v220, 16, v188
	v_and_b32_e32 v221, 0xffff0000, v188
	v_lshlrev_b32_e32 v188, 16, v189
	v_and_b32_e32 v189, 0xffff0000, v189
	v_lshlrev_b32_e32 v224, 16, v194
	v_and_b32_e32 v225, 0xffff0000, v194
	v_lshlrev_b32_e32 v194, 16, v195
	v_and_b32_e32 v195, 0xffff0000, v195
	v_lshlrev_b32_e32 v226, 16, v196
	v_and_b32_e32 v227, 0xffff0000, v196
	v_lshlrev_b32_e32 v196, 16, v197
	v_and_b32_e32 v197, 0xffff0000, v197
	v_pk_mul_f32 v[198:199], v[26:27], v[198:199] op_sel_hi:[0,1]
	v_pk_mul_f32 v[66:67], v[26:27], v[66:67] op_sel_hi:[0,1]
	v_pk_mul_f32 v[200:201], v[26:27], v[200:201] op_sel_hi:[0,1]
	v_pk_mul_f32 v[68:69], v[26:27], v[68:69] op_sel_hi:[0,1]
	v_lshlrev_b32_e32 v210, 16, v172
	v_and_b32_e32 v211, 0xffff0000, v172
	v_lshlrev_b32_e32 v172, 16, v173
	v_and_b32_e32 v173, 0xffff0000, v173
	v_lshlrev_b32_e32 v216, 16, v184
	v_and_b32_e32 v217, 0xffff0000, v184
	v_lshlrev_b32_e32 v184, 16, v185
	v_and_b32_e32 v185, 0xffff0000, v185
	v_lshlrev_b32_e32 v222, 16, v190
	v_and_b32_e32 v223, 0xffff0000, v190
	v_lshlrev_b32_e32 v190, 16, v191
	v_and_b32_e32 v191, 0xffff0000, v191
	v_lshlrev_b32_e32 v228, 16, v20
	v_and_b32_e32 v229, 0xffff0000, v20
	v_lshlrev_b32_e32 v20, 16, v21
	v_and_b32_e32 v21, 0xffff0000, v21
	v_pk_mul_f32 v[202:203], v[26:27], v[202:203] op_sel_hi:[0,1]
	v_pk_mul_f32 v[70:71], v[26:27], v[70:71] op_sel_hi:[0,1]
	v_pk_mul_f32 v[204:205], v[26:27], v[204:205] op_sel_hi:[0,1]
	v_pk_mul_f32 v[72:73], v[26:27], v[72:73] op_sel_hi:[0,1]
	v_pk_mul_f32 v[206:207], v[26:27], v[206:207] op_sel_hi:[0,1]
	v_pk_mul_f32 v[168:169], v[26:27], v[168:169] op_sel_hi:[0,1]
	v_pk_mul_f32 v[208:209], v[26:27], v[208:209] op_sel_hi:[0,1]
	v_pk_mul_f32 v[170:171], v[26:27], v[170:171] op_sel_hi:[0,1]
	v_pk_mul_f32 v[212:213], v[26:27], v[212:213] op_sel_hi:[0,1]
	v_pk_mul_f32 v[180:181], v[26:27], v[180:181] op_sel_hi:[0,1]
	v_pk_mul_f32 v[214:215], v[26:27], v[214:215] op_sel_hi:[0,1]
	v_pk_mul_f32 v[182:183], v[26:27], v[182:183] op_sel_hi:[0,1]
	v_pk_mul_f32 v[218:219], v[26:27], v[218:219] op_sel_hi:[0,1]
	v_pk_mul_f32 v[186:187], v[26:27], v[186:187] op_sel_hi:[0,1]
	v_pk_mul_f32 v[220:221], v[26:27], v[220:221] op_sel_hi:[0,1]
	v_pk_mul_f32 v[188:189], v[26:27], v[188:189] op_sel_hi:[0,1]
	v_pk_mul_f32 v[224:225], v[26:27], v[224:225] op_sel_hi:[0,1]
	v_pk_mul_f32 v[194:195], v[26:27], v[194:195] op_sel_hi:[0,1]
	v_pk_mul_f32 v[226:227], v[26:27], v[226:227] op_sel_hi:[0,1]
	v_pk_mul_f32 v[196:197], v[26:27], v[196:197] op_sel_hi:[0,1]
	v_pk_fma_f32 v[232:233], v[38:39], v[66:67], v[30:31]
	v_pk_fma_f32 v[198:199], v[36:37], v[198:199], v[28:29]
	v_pk_fma_f32 v[234:235], v[42:43], v[68:69], v[34:35]
	v_pk_fma_f32 v[200:201], v[40:41], v[200:201], v[32:33]
	v_pk_mul_f32 v[210:211], v[26:27], v[210:211] op_sel_hi:[0,1]
	v_pk_mul_f32 v[172:173], v[26:27], v[172:173] op_sel_hi:[0,1]
	v_pk_mul_f32 v[216:217], v[26:27], v[216:217] op_sel_hi:[0,1]
	v_pk_mul_f32 v[184:185], v[26:27], v[184:185] op_sel_hi:[0,1]
	v_pk_mul_f32 v[222:223], v[26:27], v[222:223] op_sel_hi:[0,1]
	v_pk_mul_f32 v[190:191], v[26:27], v[190:191] op_sel_hi:[0,1]
	v_pk_mul_f32 v[228:229], v[26:27], v[228:229] op_sel_hi:[0,1]
	v_pk_mul_f32 v[230:231], v[26:27], v[20:21] op_sel_hi:[0,1]
	v_pk_fma_f32 v[236:237], v[56:57], v[70:71], v[48:49]
	v_pk_fma_f32 v[202:203], v[54:55], v[202:203], v[46:47]
	v_pk_fma_f32 v[70:71], v[60:61], v[72:73], v[52:53]
	v_pk_fma_f32 v[72:73], v[58:59], v[204:205], v[50:51]
	v_pk_fma_f32 v[66:67], v[64:65], v[168:169], v[18:19]
	v_pk_fma_f32 v[68:69], v[62:63], v[206:207], v[16:17]
	v_pk_fma_f32 v[62:63], v[86:87], v[170:171], v[82:83]
	v_pk_fma_f32 v[64:65], v[84:85], v[208:209], v[80:81]
	v_pk_fma_f32 v[54:55], v[102:103], v[180:181], v[94:95]
	v_pk_fma_f32 v[56:57], v[100:101], v[212:213], v[92:93]
	v_pk_fma_f32 v[50:51], v[114:115], v[182:183], v[106:107]
	v_pk_fma_f32 v[52:53], v[112:113], v[214:215], v[104:105]
	v_pk_fma_f32 v[40:41], v[130:131], v[186:187], v[122:123]
	v_pk_fma_f32 v[42:43], v[128:129], v[218:219], v[120:121]
	v_pk_fma_f32 v[36:37], v[134:135], v[188:189], v[126:127]
	v_pk_fma_f32 v[38:39], v[132:133], v[220:221], v[124:125]
	v_pk_fma_f32 v[28:29], v[150:151], v[194:195], v[142:143]
	v_pk_fma_f32 v[30:31], v[148:149], v[224:225], v[140:141]
	v_pk_fma_f32 v[20:21], v[162:163], v[196:197], v[154:155]
	v_pk_fma_f32 v[26:27], v[160:161], v[226:227], v[152:153]
	v_pk_mul_f32 v[80:81], v[232:233], v[232:233]
	v_pk_mul_f32 v[82:83], v[198:199], v[198:199]
	v_pk_mul_f32 v[84:85], v[234:235], v[234:235]
	v_pk_mul_f32 v[86:87], v[200:201], v[200:201]
	v_pk_fma_f32 v[58:59], v[98:99], v[172:173], v[90:91]
	v_pk_fma_f32 v[60:61], v[96:97], v[210:211], v[88:89]
	v_pk_fma_f32 v[46:47], v[118:119], v[184:185], v[110:111]
	v_pk_fma_f32 v[48:49], v[116:117], v[216:217], v[108:109]
	v_pk_mul_f32 v[90:91], v[66:67], v[66:67]
	v_pk_mul_f32 v[92:93], v[68:69], v[68:69]
	v_mul_f32_e32 v94, v65, v65
	v_mul_f32_e32 v96, v63, v63
	v_pk_mul_f32 v[98:99], v[54:55], v[54:55]
; __device__ __forceinline__ unsigned cvt_pk_bf16(float lo, float hi) { unsigned r; asm volatile("v_cvt_pk_bf16_f32 %0, %1, %2" : "=v"(r) : "v"(lo), "v"(hi)); return r; }
; __device__ __forceinline__ float bf_lo(unsigned w) { return __uint_as_float(w << 16); }
; __device__ __forceinline__ float bf_hi(unsigned w) { return __uint_as_float(w & 0xffff0000u); }
; __device__ __forceinline__ float wave_sum(float v) {
; #pragma unroll
;     for (int o = 1; o < 64; o <<= 1) v += __shfl_xor(v, o);
;     return v;
; __device__ __forceinline__ void phase_mid(const Params& p, int gw, int NGW, int lane) {
;     ...
;         for (int j = 0; j < 16; ++j) { const u32x2 mw = mr[64 * j]; const f32x4 mo = {bf_lo(mw.x), bf_hi(mw.x), bf_lo(mw.y), bf_hi(mw.y)}; h[j] = xr[64 * j] + mo * r1 * g1p[64 * j]; ss += (h[j][0] * h[j][0] + h[j][1] * h[j][1]) + (h[j][2] * h[j][2] + h[j][3] * h[j][3]); }
;         const float r2 = rsqrtf(wave_sum(ss) * (1.f / DM) + EPSN);
;         u32x2* ho = (u32x2*)(H1 + (size_t)row * DM) + lane; u32x2* co = (u32x2*)(Cb + (size_t)row * DM) + lane;
;         asm volatile("" : "+v"(ho), "+v"(co));
; #pragma unroll
;         for (int j = 0; j < 16; ++j) { { u32x2 hw; hw.x = cvt_pk_bf16(h[j][0], h[j][1]); hw.y = cvt_pk_bf16(h[j][2], h[j][3]); ho[64 * j] = hw; } const f32x4 c = h[j] * r2 * g2p[64 * j]; u32x2 w; w.x = cvt_pk_bf16(c[0], c[1]); w.y = cvt_pk_bf16(c[2], c[3]); co[64 * j] = w; }
	v_pk_mul_f32 v[100:101], v[56:57], v[56:57]
	v_mul_f32_e32 v102, v53, v53
	v_mul_f32_e32 v104, v51, v51
	v_pk_mul_f32 v[106:107], v[40:41], v[40:41]
	v_pk_mul_f32 v[108:109], v[42:43], v[42:43]
	v_mul_f32_e32 v110, v39, v39
	v_mul_f32_e32 v112, v37, v37
	v_pk_mul_f32 v[114:115], v[28:29], v[28:29]
	v_pk_mul_f32 v[116:117], v[30:31], v[30:31]
	v_mul_f32_e32 v118, v27, v27
	v_mul_f32_e32 v120, v21, v21
	v_cvt_pk_bf16_f32 v122, v198, v199
	v_cvt_pk_bf16_f32 v123, v232, v233
	v_pk_mov_b32 v[124:125], v[82:83], v[80:81] op_sel:[1,0]
	v_mov_b32_e32 v83, v81
	v_pk_mov_b32 v[80:81], v[86:87], v[84:85] op_sel:[1,0]
	v_mov_b32_e32 v87, v85
	global_store_dwordx2 v[24:25], v[122:123], off
	v_pk_mov_b32 v[126:127], v[92:93], v[90:91] op_sel:[1,0]
	v_mov_b32_e32 v93, v91
	v_pk_fma_f32 v[90:91], v[64:65], v[64:65], v[94:95] op_sel_hi:[1,1,0]
	v_pk_fma_f32 v[94:95], v[62:63], v[62:63], v[96:97] op_sel_hi:[1,1,0]
	v_pk_mov_b32 v[96:97], v[100:101], v[98:99] op_sel:[1,0]
	v_mov_b32_e32 v101, v99
	v_pk_fma_f32 v[98:99], v[52:53], v[52:53], v[102:103] op_sel_hi:[1,1,0]
	v_pk_fma_f32 v[102:103], v[50:51], v[50:51], v[104:105] op_sel_hi:[1,1,0]
	v_pk_mov_b32 v[104:105], v[108:109], v[106:107] op_sel:[1,0]
	v_mov_b32_e32 v109, v107
	v_pk_fma_f32 v[106:107], v[38:39], v[38:39], v[110:111] op_sel_hi:[1,1,0]
	v_pk_fma_f32 v[110:111], v[36:37], v[36:37], v[112:113] op_sel_hi:[1,1,0]
	v_pk_mov_b32 v[112:113], v[116:117], v[114:115] op_sel:[1,0]
	v_mov_b32_e32 v117, v115
	v_pk_fma_f32 v[114:115], v[26:27], v[26:27], v[118:119] op_sel_hi:[1,1,0]
	v_pk_fma_f32 v[118:119], v[20:21], v[20:21], v[120:121] op_sel_hi:[1,1,0]
	v_pk_add_f32 v[120:121], v[124:125], v[82:83]
	v_pk_add_f32 v[86:87], v[80:81], v[86:87]
	global_load_dwordx4 v[80:83], v176, s[24:25]
	global_load_dwordx4 v[122:125], v176, s[24:25] offset:1024
	global_load_dwordx4 v[148:151], v176, s[24:25] offset:2048
	global_load_dwordx4 v[152:155], v176, s[24:25] offset:3072
	v_add_u32_e32 v172, 0x1000, v176
	global_load_dwordx4 v[160:163], v172, s[24:25]
	global_load_dwordx4 v[168:171], v172, s[24:25] offset:1024
	global_load_dwordx4 v[180:183], v172, s[24:25] offset:2048
	global_load_dwordx4 v[184:187], v172, s[24:25] offset:3072
	v_add_u32_e32 v173, 0x2000, v176
	global_load_dwordx4 v[194:197], v173, s[24:25]
	global_load_dwordx4 v[204:207], v173, s[24:25] offset:1024
	global_load_dwordx4 v[208:211], v173, s[24:25] offset:2048
	global_load_dwordx4 v[212:215], v173, s[24:25] offset:3072
	v_add_u32_e32 v188, 0x3000, v176
	global_load_dwordx4 v[216:219], v188, s[24:25]
	global_load_dwordx4 v[224:227], v188, s[24:25] offset:1024
	global_load_dwordx4 v[238:241], v188, s[24:25] offset:2048
	global_load_dwordx4 v[242:245], v188, s[24:25] offset:3072
	v_mul_f32_e32 v44, v203, v203
	v_mul_f32_e32 v88, v237, v237
	v_mul_f32_e32 v128, v72, v72
	v_mul_f32_e32 v129, v73, v73
	v_mul_f32_e32 v130, v70, v70
	v_mul_f32_e32 v131, v71, v71
	v_pk_fma_f32 v[84:85], v[202:203], v[202:203], v[44:45] op_sel_hi:[1,1,0]
	v_pk_fma_f32 v[88:89], v[236:237], v[236:237], v[88:89] op_sel_hi:[1,1,0]
	v_pk_add_f32 v[96:97], v[96:97], v[100:101]
	v_pk_add_f32 v[100:101], v[104:105], v[108:109]
	v_pk_add_f32 v[108:109], v[120:121], v[120:121] op_sel:[0,1] op_sel_hi:[1,0]
	v_pk_add_f32 v[86:87], v[86:87], v[86:87] op_sel:[0,1] op_sel_hi:[1,0]
	v_mov_b32_e32 v85, v130
	v_mov_b32_e32 v89, v131
	v_mov_b32_e32 v109, v128
	v_mov_b32_e32 v87, v129
	v_pk_add_f32 v[84:85], v[84:85], v[88:89]
	v_pk_add_f32 v[86:87], v[108:109], v[86:87]
	v_pk_add_f32 v[92:93], v[126:127], v[92:93]
	v_pk_add_f32 v[84:85], v[86:87], v[84:85]
	v_mul_f32_e32 v132, v60, v60
	v_mul_f32_e32 v133, v61, v61
	v_mul_f32_e32 v134, v58, v58
	v_mul_f32_e32 v135, v59, v59
	v_pk_add_f32 v[88:89], v[92:93], v[92:93] op_sel:[0,1] op_sel_hi:[1,0]
	v_pk_add_f32 v[84:85], v[84:85], v[84:85] op_sel:[0,1] op_sel_hi:[1,0]
	v_mov_b32_e32 v91, v134
	v_mov_b32_e32 v95, v135
	v_mov_b32_e32 v89, v133
	v_mov_b32_e32 v85, v132
	v_pk_add_f32 v[90:91], v[90:91], v[94:95]
	v_pk_add_f32 v[84:85], v[84:85], v[88:89]
	v_pk_fma_f32 v[32:33], v[146:147], v[190:191], v[138:139]
	v_pk_add_f32 v[84:85], v[84:85], v[90:91]
	v_pk_fma_f32 v[34:35], v[144:145], v[222:223], v[136:137]
	v_mul_f32_e32 v136, v48, v48
	v_mul_f32_e32 v137, v49, v49
	v_mul_f32_e32 v138, v46, v46
	v_mul_f32_e32 v139, v47, v47
	v_pk_add_f32 v[92:93], v[96:97], v[96:97] op_sel:[0,1] op_sel_hi:[1,0]
	v_pk_add_f32 v[84:85], v[84:85], v[84:85] op_sel:[0,1] op_sel_hi:[1,0]
	v_mov_b32_e32 v99, v138
	v_mov_b32_e32 v103, v139
	v_mov_b32_e32 v93, v137
	v_mov_b32_e32 v85, v136
	v_pk_add_f32 v[94:95], v[98:99], v[102:103]
	v_pk_add_f32 v[84:85], v[84:85], v[92:93]
	v_mul_f32_e32 v140, v34, v34
	v_pk_add_f32 v[84:85], v[84:85], v[94:95]
	v_mul_f32_e32 v141, v35, v35
	v_mul_f32_e32 v142, v32, v32
	v_mul_f32_e32 v143, v33, v33
	v_pk_add_f32 v[96:97], v[100:101], v[100:101] op_sel:[0,1] op_sel_hi:[1,0]
	v_pk_add_f32 v[84:85], v[84:85], v[84:85] op_sel:[0,1] op_sel_hi:[1,0]
	v_mov_b32_e32 v107, v142
	v_mov_b32_e32 v111, v143
	v_mov_b32_e32 v97, v141
	v_mov_b32_e32 v85, v140
	v_pk_add_f32 v[98:99], v[106:107], v[110:111]
	v_pk_add_f32 v[84:85], v[84:85], v[96:97]
	v_pk_fma_f32 v[16:17], v[166:167], v[230:231], v[158:159]
	v_pk_fma_f32 v[18:19], v[164:165], v[228:229], v[156:157]
	v_pk_add_f32 v[104:105], v[112:113], v[116:117]
	v_pk_add_f32 v[84:85], v[84:85], v[98:99]
	v_mul_f32_e32 v144, v18, v18
	v_mul_f32_e32 v145, v19, v19
	v_mul_f32_e32 v146, v16, v16
	v_mul_f32_e32 v147, v17, v17
	v_pk_add_f32 v[100:101], v[104:105], v[104:105] op_sel:[0,1] op_sel_hi:[1,0]
	v_pk_add_f32 v[84:85], v[84:85], v[84:85] op_sel:[0,1] op_sel_hi:[1,0]
	v_mov_b32_e32 v115, v146
	v_mov_b32_e32 v119, v147
	v_mov_b32_e32 v101, v145
	v_mov_b32_e32 v85, v144
	v_pk_add_f32 v[102:103], v[114:115], v[118:119]
	v_pk_add_f32 v[84:85], v[84:85], v[100:101]
	s_nop 0
	v_pk_add_f32 v[84:85], v[84:85], v[102:103]
	s_nop 0
	v_add_f32_e32 v44, v84, v85
	s_nop 1
	v_add_f32_dpp v44, v44, v44 quad_perm:[1,0,3,2] row_mask:0xf bank_mask:0xf
	s_nop 1
	v_add_f32_dpp v44, v44, v44 quad_perm:[2,3,0,1] row_mask:0xf bank_mask:0xf
	s_nop 1
	v_add_f32_dpp v44, v44, v44 row_half_mirror row_mask:0xf bank_mask:0xf
	s_nop 1
	v_add_f32_dpp v44, v44, v44 row_mirror row_mask:0xf bank_mask:0xf
	s_nop 1
	v_add_f32_dpp v44, v44, v44 row_bcast:15 row_mask:0xa bank_mask:0xf
	s_nop 1
	v_add_f32_dpp v44, v44, v44 row_bcast:31 row_mask:0xc bank_mask:0xf
	s_nop 1
	v_readlane_b32 vcc_lo, v44, 63
	s_nop 1
	v_mov_b32_e32 v44, vcc_lo
	v_fmamk_f32 v44, v44, 0x39800000, v79
	v_mul_f32_e32 v84, 0x4b800000, v44
	v_cmp_gt_f32_e32 vcc, s8, v44
	s_nop 1
	v_cndmask_b32_e32 v44, v44, v84, vcc
	v_rsq_f32_e32 v44, v44
	s_nop 0
	v_mul_f32_e32 v84, 0x45800000, v44
	v_cndmask_b32_e32 v44, v44, v84, vcc
	v_pk_mul_f32 v[84:85], v[198:199], v[44:45] op_sel_hi:[1,0]
	v_pk_mul_f32 v[86:87], v[232:233], v[44:45] op_sel_hi:[1,0]
	s_waitcnt vmcnt(0)
; __device__ __forceinline__ unsigned cvt_pk_bf16(float lo, float hi) { unsigned r; asm volatile("v_cvt_pk_bf16_f32 %0, %1, %2" : "=v"(r) : "v"(lo), "v"(hi)); return r; }
; __device__ __forceinline__ void phase_mid(const Params& p, int gw, int NGW, int lane) {
;     ...
; #pragma unroll
;         for (int j = 0; j < 16; ++j) { { u32x2 hw; hw.x = cvt_pk_bf16(h[j][0], h[j][1]); hw.y = cvt_pk_bf16(h[j][2], h[j][3]); ho[64 * j] = hw; } const f32x4 c = h[j] * r2 * g2p[64 * j]; u32x2 w; w.x = cvt_pk_bf16(c[0], c[1]); w.y = cvt_pk_bf16(c[2], c[3]); co[64 * j] = w; }
	v_pk_mul_f32 v[80:81], v[80:81], v[84:85]
	v_pk_mul_f32 v[82:83], v[82:83], v[86:87]
	v_cvt_pk_bf16_f32 v80, v80, v81
	v_pk_mul_f32 v[84:85], v[200:201], v[44:45] op_sel_hi:[1,0]
	v_cvt_pk_bf16_f32 v81, v82, v83
	global_store_dwordx2 v[22:23], v[80:81], off
	v_cvt_pk_bf16_f32 v80, v200, v201
	v_cvt_pk_bf16_f32 v81, v234, v235
	global_store_dwordx2 v[24:25], v[80:81], off offset:512
	v_mov_b64_e32 v[80:81], v[122:123]
	v_mov_b64_e32 v[82:83], v[124:125]
	v_pk_mul_f32 v[86:87], v[234:235], v[44:45] op_sel_hi:[1,0]
	v_pk_mul_f32 v[80:81], v[80:81], v[84:85]
	v_pk_mul_f32 v[82:83], v[82:83], v[86:87]
	v_cvt_pk_bf16_f32 v80, v80, v81
	v_pk_mul_f32 v[84:85], v[202:203], v[44:45] op_sel_hi:[1,0]
	v_cvt_pk_bf16_f32 v81, v82, v83
	global_store_dwordx2 v[22:23], v[80:81], off offset:512
	v_cvt_pk_bf16_f32 v80, v202, v203
	v_cvt_pk_bf16_f32 v81, v236, v237
	global_store_dwordx2 v[24:25], v[80:81], off offset:1024
	v_mov_b64_e32 v[80:81], v[148:149]
	v_mov_b64_e32 v[82:83], v[150:151]
	v_pk_mul_f32 v[86:87], v[236:237], v[44:45] op_sel_hi:[1,0]
	v_pk_mul_f32 v[80:81], v[80:81], v[84:85]
	v_pk_mul_f32 v[82:83], v[82:83], v[86:87]
	v_cvt_pk_bf16_f32 v80, v80, v81
	v_cvt_pk_bf16_f32 v81, v82, v83
	global_store_dwordx2 v[22:23], v[80:81], off offset:1024
	v_cvt_pk_bf16_f32 v80, v72, v73
	v_cvt_pk_bf16_f32 v81, v70, v71
	global_store_dwordx2 v[24:25], v[80:81], off offset:1536
	v_mov_b64_e32 v[80:81], v[152:153]
	v_mov_b64_e32 v[82:83], v[154:155]
	v_pk_mul_f32 v[72:73], v[72:73], v[44:45] op_sel_hi:[1,0]
	v_pk_mul_f32 v[70:71], v[70:71], v[44:45] op_sel_hi:[1,0]
	v_pk_mul_f32 v[70:71], v[70:71], v[82:83]
	v_pk_mul_f32 v[72:73], v[72:73], v[80:81]
	s_nop 0
	v_cvt_pk_bf16_f32 v72, v72, v73
	v_cvt_pk_bf16_f32 v73, v70, v71
	global_store_dwordx2 v[22:23], v[72:73], off offset:1536
	v_cvt_pk_bf16_f32 v70, v68, v69
	v_cvt_pk_bf16_f32 v71, v66, v67
	global_store_dwordx2 v[24:25], v[70:71], off offset:2048
	v_mov_b64_e32 v[70:71], v[160:161]
	v_mov_b64_e32 v[72:73], v[162:163]
	v_pk_mul_f32 v[68:69], v[68:69], v[44:45] op_sel_hi:[1,0]
	v_pk_mul_f32 v[66:67], v[66:67], v[44:45] op_sel_hi:[1,0]
	v_pk_mul_f32 v[68:69], v[68:69], v[70:71]
	v_pk_mul_f32 v[66:67], v[66:67], v[72:73]
	v_cvt_pk_bf16_f32 v68, v68, v69
	s_nop 0
	v_cvt_pk_bf16_f32 v69, v66, v67
	global_store_dwordx2 v[22:23], v[68:69], off offset:2048
	v_cvt_pk_bf16_f32 v66, v64, v65
	v_cvt_pk_bf16_f32 v67, v62, v63
	global_store_dwordx2 v[24:25], v[66:67], off offset:2560
	v_mov_b64_e32 v[66:67], v[168:169]
	v_mov_b64_e32 v[68:69], v[170:171]
	v_pk_mul_f32 v[64:65], v[64:65], v[44:45] op_sel_hi:[1,0]
	v_pk_mul_f32 v[62:63], v[62:63], v[44:45] op_sel_hi:[1,0]
	v_pk_mul_f32 v[64:65], v[64:65], v[66:67]
	v_pk_mul_f32 v[62:63], v[62:63], v[68:69]
	v_cvt_pk_bf16_f32 v64, v64, v65
	s_nop 0
	v_cvt_pk_bf16_f32 v65, v62, v63
	global_store_dwordx2 v[22:23], v[64:65], off offset:2560
	v_cvt_pk_bf16_f32 v62, v60, v61
	v_cvt_pk_bf16_f32 v63, v58, v59
	global_store_dwordx2 v[24:25], v[62:63], off offset:3072
	v_mov_b64_e32 v[62:63], v[180:181]
	v_mov_b64_e32 v[64:65], v[182:183]
	v_pk_mul_f32 v[60:61], v[60:61], v[44:45] op_sel_hi:[1,0]
	v_pk_mul_f32 v[58:59], v[58:59], v[44:45] op_sel_hi:[1,0]
	v_pk_mul_f32 v[60:61], v[60:61], v[62:63]
	v_pk_mul_f32 v[58:59], v[58:59], v[64:65]
	v_cvt_pk_bf16_f32 v60, v60, v61
	v_cvt_pk_bf16_f32 v61, v58, v59
	global_store_dwordx2 v[22:23], v[60:61], off offset:3072
	v_cvt_pk_bf16_f32 v58, v56, v57
	v_cvt_pk_bf16_f32 v59, v54, v55
	global_store_dwordx2 v[24:25], v[58:59], off offset:3584
	v_mov_b64_e32 v[58:59], v[184:185]
	v_mov_b64_e32 v[60:61], v[186:187]
	v_add_co_u32_e32 v64, vcc, s9, v24
	v_pk_mul_f32 v[54:55], v[54:55], v[44:45] op_sel_hi:[1,0]
	s_nop 0
	v_addc_co_u32_e32 v65, vcc, 0, v25, vcc
	v_pk_mul_f32 v[24:25], v[56:57], v[44:45] op_sel_hi:[1,0]
	v_pk_mul_f32 v[54:55], v[54:55], v[60:61]
	v_pk_mul_f32 v[24:25], v[24:25], v[58:59]
	v_add_co_u32_e32 v58, vcc, s9, v22
	v_cvt_pk_bf16_f32 v24, v24, v25
	v_cvt_pk_bf16_f32 v25, v54, v55
	global_store_dwordx2 v[22:23], v[24:25], off offset:3584
	v_cvt_pk_bf16_f32 v24, v52, v53
	v_cvt_pk_bf16_f32 v25, v50, v51
	global_store_dwordx2 v[64:65], v[24:25], off
	v_mov_b64_e32 v[54:55], v[194:195]
; __device__ __forceinline__ unsigned cvt_pk_bf16(float lo, float hi) { unsigned r; asm volatile("v_cvt_pk_bf16_f32 %0, %1, %2" : "=v"(r) : "v"(lo), "v"(hi)); return r; }
; __device__ __forceinline__ void phase_mid(const Params& p, int gw, int NGW, int lane) {
;     ...
; #pragma unroll
;         for (int j = 0; j < 16; ++j) { { u32x2 hw; hw.x = cvt_pk_bf16(h[j][0], h[j][1]); hw.y = cvt_pk_bf16(h[j][2], h[j][3]); ho[64 * j] = hw; } const f32x4 c = h[j] * r2 * g2p[64 * j]; u32x2 w; w.x = cvt_pk_bf16(c[0], c[1]); w.y = cvt_pk_bf16(c[2], c[3]); co[64 * j] = w; }
;     }
	v_mov_b64_e32 v[56:57], v[196:197]
	v_addc_co_u32_e32 v59, vcc, 0, v23, vcc
	v_pk_mul_f32 v[22:23], v[52:53], v[44:45] op_sel_hi:[1,0]
	v_pk_mul_f32 v[24:25], v[50:51], v[44:45] op_sel_hi:[1,0]
	v_pk_mul_f32 v[22:23], v[22:23], v[54:55]
	v_pk_mul_f32 v[24:25], v[24:25], v[56:57]
	v_cvt_pk_bf16_f32 v22, v22, v23
	v_cvt_pk_bf16_f32 v23, v24, v25
	global_store_dwordx2 v[58:59], v[22:23], off
	v_cvt_pk_bf16_f32 v22, v48, v49
	v_cvt_pk_bf16_f32 v23, v46, v47
	global_store_dwordx2 v[64:65], v[22:23], off offset:512
	v_mov_b64_e32 v[22:23], v[204:205]
	v_mov_b64_e32 v[24:25], v[206:207]
	v_pk_mul_f32 v[48:49], v[48:49], v[44:45] op_sel_hi:[1,0]
	v_pk_mul_f32 v[46:47], v[46:47], v[44:45] op_sel_hi:[1,0]
	v_pk_mul_f32 v[22:23], v[48:49], v[22:23]
	v_pk_mul_f32 v[24:25], v[46:47], v[24:25]
	v_cvt_pk_bf16_f32 v22, v22, v23
	s_nop 0
	v_cvt_pk_bf16_f32 v23, v24, v25
	global_store_dwordx2 v[58:59], v[22:23], off offset:512
	v_cvt_pk_bf16_f32 v22, v42, v43
	v_cvt_pk_bf16_f32 v23, v40, v41
	global_store_dwordx2 v[64:65], v[22:23], off offset:1024
	v_mov_b64_e32 v[22:23], v[208:209]
	v_mov_b64_e32 v[24:25], v[210:211]
	v_pk_mul_f32 v[42:43], v[42:43], v[44:45] op_sel_hi:[1,0]
	v_pk_mul_f32 v[40:41], v[40:41], v[44:45] op_sel_hi:[1,0]
	v_pk_mul_f32 v[22:23], v[42:43], v[22:23]
	v_pk_mul_f32 v[24:25], v[40:41], v[24:25]
	v_cvt_pk_bf16_f32 v22, v22, v23
	s_nop 0
	v_cvt_pk_bf16_f32 v23, v24, v25
	global_store_dwordx2 v[58:59], v[22:23], off offset:1024
	v_cvt_pk_bf16_f32 v22, v38, v39
	v_cvt_pk_bf16_f32 v23, v36, v37
	global_store_dwordx2 v[64:65], v[22:23], off offset:1536
	v_mov_b64_e32 v[22:23], v[212:213]
	v_mov_b64_e32 v[24:25], v[214:215]
	v_pk_mul_f32 v[38:39], v[38:39], v[44:45] op_sel_hi:[1,0]
	v_pk_mul_f32 v[36:37], v[36:37], v[44:45] op_sel_hi:[1,0]
	v_pk_mul_f32 v[22:23], v[38:39], v[22:23]
	v_pk_mul_f32 v[24:25], v[36:37], v[24:25]
	v_cvt_pk_bf16_f32 v22, v22, v23
	s_nop 0
	v_cvt_pk_bf16_f32 v23, v24, v25
	global_store_dwordx2 v[58:59], v[22:23], off offset:1536
	v_cvt_pk_bf16_f32 v22, v34, v35
	v_cvt_pk_bf16_f32 v23, v32, v33
	global_store_dwordx2 v[64:65], v[22:23], off offset:2048
	v_mov_b64_e32 v[22:23], v[216:217]
	v_mov_b64_e32 v[24:25], v[218:219]
	v_pk_mul_f32 v[34:35], v[34:35], v[44:45] op_sel_hi:[1,0]
	v_pk_mul_f32 v[32:33], v[32:33], v[44:45] op_sel_hi:[1,0]
	v_pk_mul_f32 v[22:23], v[34:35], v[22:23]
	v_pk_mul_f32 v[24:25], v[32:33], v[24:25]
	v_cvt_pk_bf16_f32 v22, v22, v23
	s_nop 0
	v_cvt_pk_bf16_f32 v23, v24, v25
	global_store_dwordx2 v[58:59], v[22:23], off offset:2048
	v_cvt_pk_bf16_f32 v22, v30, v31
	v_cvt_pk_bf16_f32 v23, v28, v29
	global_store_dwordx2 v[64:65], v[22:23], off offset:2560
	v_mov_b64_e32 v[22:23], v[224:225]
	v_mov_b64_e32 v[24:25], v[226:227]
	v_pk_mul_f32 v[30:31], v[30:31], v[44:45] op_sel_hi:[1,0]
	v_pk_mul_f32 v[28:29], v[28:29], v[44:45] op_sel_hi:[1,0]
	v_pk_mul_f32 v[22:23], v[30:31], v[22:23]
	v_pk_mul_f32 v[24:25], v[28:29], v[24:25]
	v_cvt_pk_bf16_f32 v22, v22, v23
	s_nop 0
	v_cvt_pk_bf16_f32 v23, v24, v25
	global_store_dwordx2 v[58:59], v[22:23], off offset:2560
	v_cvt_pk_bf16_f32 v22, v26, v27
	v_cvt_pk_bf16_f32 v23, v20, v21
	global_store_dwordx2 v[64:65], v[22:23], off offset:3072
	v_mov_b64_e32 v[22:23], v[238:239]
	v_mov_b64_e32 v[24:25], v[240:241]
	v_pk_mul_f32 v[26:27], v[26:27], v[44:45] op_sel_hi:[1,0]
	v_pk_mul_f32 v[20:21], v[20:21], v[44:45] op_sel_hi:[1,0]
	v_pk_mul_f32 v[22:23], v[26:27], v[22:23]
	v_pk_mul_f32 v[20:21], v[20:21], v[24:25]
	v_cvt_pk_bf16_f32 v22, v22, v23
	s_nop 0
	v_cvt_pk_bf16_f32 v23, v20, v21
	global_store_dwordx2 v[58:59], v[22:23], off offset:3072
	v_cvt_pk_bf16_f32 v20, v18, v19
	v_cvt_pk_bf16_f32 v21, v16, v17
	global_store_dwordx2 v[64:65], v[20:21], off offset:3584
	v_mov_b64_e32 v[20:21], v[242:243]
	v_mov_b64_e32 v[22:23], v[244:245]
	v_pk_mul_f32 v[14:15], v[18:19], v[44:45] op_sel_hi:[1,0]
	v_pk_mul_f32 v[16:17], v[16:17], v[44:45] op_sel_hi:[1,0]
	v_pk_mul_f32 v[14:15], v[14:15], v[20:21]
	v_pk_mul_f32 v[16:17], v[16:17], v[22:23]
	v_cvt_pk_bf16_f32 v14, v14, v15
	s_nop 0
	v_cvt_pk_bf16_f32 v15, v16, v17
	global_store_dwordx2 v[58:59], v[14:15], off offset:3584
	s_cbranch_scc1 .LBB0_711
